# v25 + prep x->bf16 copy loop: four 32-byte items per thread requested together before the first conversion (was one item per iteration, waited for immediately)
# speedup vs baseline: 1.0335x; 1.0055x over previous
.Lmy_prep_u4:
	v_lshl_add_u64 v[98:99], v[2:3], 0, s[14:15]
	v_lshl_add_u64 v[98:99], v[98:99], 0, s[14:15]
	v_lshl_add_u64 v[98:99], v[98:99], 0, s[14:15]
	v_cmp_lt_u64_e32 vcc, s[22:23], v[98:99]
	s_and_b64 vcc, vcc, exec
	s_cbranch_vccnz .Lmy_prep_tail
	v_lshl_add_u64 v[92:93], v[6:7], 0, s[18:19]
	v_lshl_add_u64 v[94:95], v[92:93], 0, s[18:19]
	v_lshl_add_u64 v[96:97], v[94:95], 0, s[18:19]
	global_load_dwordx4 v[60:63], v[6:7], off offset:-16 nt
	global_load_dwordx4 v[64:67], v[6:7], off nt
	global_load_dwordx4 v[68:71], v[92:93], off offset:-16 nt
	global_load_dwordx4 v[72:75], v[92:93], off nt
	global_load_dwordx4 v[76:79], v[94:95], off offset:-16 nt
	global_load_dwordx4 v[80:83], v[94:95], off nt
	global_load_dwordx4 v[84:87], v[96:97], off offset:-16 nt
	global_load_dwordx4 v[88:91], v[96:97], off nt
	v_lshl_add_u64 v[6:7], v[96:97], 0, s[18:19]
	v_lshl_add_u64 v[2:3], v[98:99], 0, s[14:15]
	s_waitcnt vmcnt(6)
	v_cvt_pk_bf16_f32 v60, v60, v61
	v_cvt_pk_bf16_f32 v61, v62, v63
	v_cvt_pk_bf16_f32 v62, v64, v65
	v_cvt_pk_bf16_f32 v63, v66, v67
	global_store_dwordx4 v[4:5], v[60:63], off sc0 sc1
	v_lshl_add_u64 v[4:5], v[4:5], 0, s[16:17]
	s_waitcnt vmcnt(5)
	v_cvt_pk_bf16_f32 v68, v68, v69
	v_cvt_pk_bf16_f32 v69, v70, v71
	v_cvt_pk_bf16_f32 v70, v72, v73
	v_cvt_pk_bf16_f32 v71, v74, v75
	global_store_dwordx4 v[4:5], v[68:71], off sc0 sc1
	v_lshl_add_u64 v[4:5], v[4:5], 0, s[16:17]
	s_waitcnt vmcnt(4)
	v_cvt_pk_bf16_f32 v76, v76, v77
	v_cvt_pk_bf16_f32 v77, v78, v79
	v_cvt_pk_bf16_f32 v78, v80, v81
	v_cvt_pk_bf16_f32 v79, v82, v83
	global_store_dwordx4 v[4:5], v[76:79], off sc0 sc1
	v_lshl_add_u64 v[4:5], v[4:5], 0, s[16:17]
	s_waitcnt vmcnt(3)
	v_cvt_pk_bf16_f32 v84, v84, v85
	v_cvt_pk_bf16_f32 v85, v86, v87
	v_cvt_pk_bf16_f32 v86, v88, v89
	v_cvt_pk_bf16_f32 v87, v90, v91
	global_store_dwordx4 v[4:5], v[84:87], off sc0 sc1
	v_lshl_add_u64 v[4:5], v[4:5], 0, s[16:17]
	s_branch .Lmy_prep_u4
.Lmy_prep_tail:
	v_cmp_ge_u64_e32 vcc, s[22:23], v[2:3]
	s_and_b64 exec, exec, vcc
	s_cbranch_execz .LBB0_46
